# ml_seq: q.n operand row replicated to rows 0,4,8,12 so the epilogue needs no cross-lane broadcast
# speedup vs baseline: 1.0040x; 1.0040x over previous
.LBB0_797:
	s_and_saveexec_b64 s[22:23], s[6:7]
	s_cbranch_execz .LBB0_805
	v_cndmask_b32_e64 v102, 0, 1, s[20:21]
	s_movk_i32 s24, 0x440
	v_mul_lo_u32 v103, v102, s24
	s_mov_b32 s24, 0x8200
	v_mul_lo_u32 v102, v102, s24
	v_add_u32_e32 v227, v177, v103
	v_add_u32_e32 v226, v190, v102
	v_add_u32_e32 v227, 0x20800, v227
	v_add_u32_e32 v226, 0x10400, v226
	v_and_b32_e32 v228, 3, v154
	v_cmp_eq_u32_e64 s[64:65], 0, v228
	v_mov_b32_e32 v130, 0
	v_mov_b32_e32 v131, 0
	v_mov_b32_e32 v132, 0
	v_mov_b32_e32 v133, 0
	v_mov_b32_e32 v206, 0
	v_mov_b32_e32 v207, 0
	v_mov_b32_e32 v208, 0
	v_mov_b32_e32 v209, 0
	v_mov_b32_e32 v222, 0
	v_mov_b32_e32 v223, 0
	v_mov_b32_e32 v224, 0
	v_mov_b32_e32 v225, 0
	ds_read_b128 v[118:121], v160
	ds_read_b128 v[122:125], v160 offset:16640
	ds_read_b128 v[126:129], v226
	s_and_saveexec_b64 s[24:25], s[64:65]
	ds_read_b128 v[130:133], v227
	s_or_b64 exec, exec, s[24:25]
	ds_read_b128 v[194:197], v160 offset:64
	ds_read_b128 v[198:201], v160 offset:16704
	ds_read_b128 v[202:205], v226 offset:64
	s_and_saveexec_b64 s[24:25], s[64:65]
	ds_read_b128 v[206:209], v227 offset:64
	s_or_b64 exec, exec, s[24:25]
	v_mov_b32_e32 v102, 0
	v_mov_b32_e32 v103, 0
	v_mov_b32_e32 v104, 0
	v_mov_b32_e32 v105, 0
	v_mov_b32_e32 v106, 0
	v_mov_b32_e32 v107, 0
	v_mov_b32_e32 v108, 0
	v_mov_b32_e32 v109, 0
	v_mov_b32_e32 v110, 0
	v_mov_b32_e32 v111, 0
	v_mov_b32_e32 v112, 0
	v_mov_b32_e32 v113, 0
	v_mov_b32_e32 v114, 0
	v_mov_b32_e32 v115, 0
	v_mov_b32_e32 v116, 0
	v_mov_b32_e32 v117, 0
	s_waitcnt lgkmcnt(4)
	v_mfma_f32_16x16x32_bf16 v[110:113], v[126:129], v[118:121], v[110:113]
	v_mfma_f32_16x16x32_bf16 v[114:117], v[130:133], v[118:121], v[114:117]
	v_mfma_f32_16x16x32_bf16 v[102:105], v[126:129], v[122:125], v[102:105]
	v_mfma_f32_16x16x32_bf16 v[106:109], v[130:133], v[122:125], v[106:109]
	ds_read_b128 v[210:213], v160 offset:128
	ds_read_b128 v[214:217], v160 offset:16768
	ds_read_b128 v[218:221], v226 offset:128
	s_and_saveexec_b64 s[24:25], s[64:65]
	ds_read_b128 v[222:225], v227 offset:128
	s_or_b64 exec, exec, s[24:25]
	s_waitcnt lgkmcnt(4)
	v_mfma_f32_16x16x32_bf16 v[110:113], v[202:205], v[194:197], v[110:113]
	v_mfma_f32_16x16x32_bf16 v[114:117], v[206:209], v[194:197], v[114:117]
	v_mfma_f32_16x16x32_bf16 v[102:105], v[202:205], v[198:201], v[102:105]
	v_mfma_f32_16x16x32_bf16 v[106:109], v[206:209], v[198:201], v[106:109]
	ds_read_b128 v[118:121], v160 offset:192
	ds_read_b128 v[122:125], v160 offset:16832
	ds_read_b128 v[126:129], v226 offset:192
	s_and_saveexec_b64 s[24:25], s[64:65]
	ds_read_b128 v[130:133], v227 offset:192
	s_or_b64 exec, exec, s[24:25]
	s_waitcnt lgkmcnt(4)
	v_mfma_f32_16x16x32_bf16 v[110:113], v[218:221], v[210:213], v[110:113]
	v_mfma_f32_16x16x32_bf16 v[114:117], v[222:225], v[210:213], v[114:117]
	v_mfma_f32_16x16x32_bf16 v[102:105], v[218:221], v[214:217], v[102:105]
	v_mfma_f32_16x16x32_bf16 v[106:109], v[222:225], v[214:217], v[106:109]
	ds_read_b128 v[194:197], v160 offset:256
	ds_read_b128 v[198:201], v160 offset:16896
	ds_read_b128 v[202:205], v226 offset:256
	s_and_saveexec_b64 s[24:25], s[64:65]
	ds_read_b128 v[206:209], v227 offset:256
	s_or_b64 exec, exec, s[24:25]
	s_waitcnt lgkmcnt(4)
	v_mfma_f32_16x16x32_bf16 v[110:113], v[126:129], v[118:121], v[110:113]
	v_mfma_f32_16x16x32_bf16 v[114:117], v[130:133], v[118:121], v[114:117]
	v_mfma_f32_16x16x32_bf16 v[102:105], v[126:129], v[122:125], v[102:105]
	v_mfma_f32_16x16x32_bf16 v[106:109], v[130:133], v[122:125], v[106:109]
	ds_read_b128 v[210:213], v160 offset:320
	ds_read_b128 v[214:217], v160 offset:16960
	ds_read_b128 v[218:221], v226 offset:320
	s_and_saveexec_b64 s[24:25], s[64:65]
	ds_read_b128 v[222:225], v227 offset:320
	s_or_b64 exec, exec, s[24:25]
	s_waitcnt lgkmcnt(4)
	v_mfma_f32_16x16x32_bf16 v[110:113], v[202:205], v[194:197], v[110:113]
	v_mfma_f32_16x16x32_bf16 v[114:117], v[206:209], v[194:197], v[114:117]
	v_mfma_f32_16x16x32_bf16 v[102:105], v[202:205], v[198:201], v[102:105]
	v_mfma_f32_16x16x32_bf16 v[106:109], v[206:209], v[198:201], v[106:109]
	ds_read_b128 v[118:121], v160 offset:384
	ds_read_b128 v[122:125], v160 offset:17024
	ds_read_b128 v[126:129], v226 offset:384
	s_and_saveexec_b64 s[24:25], s[64:65]
	ds_read_b128 v[130:133], v227 offset:384
	s_or_b64 exec, exec, s[24:25]
	s_waitcnt lgkmcnt(4)
	v_mfma_f32_16x16x32_bf16 v[110:113], v[218:221], v[210:213], v[110:113]
	v_mfma_f32_16x16x32_bf16 v[114:117], v[222:225], v[210:213], v[114:117]
	v_mfma_f32_16x16x32_bf16 v[102:105], v[218:221], v[214:217], v[102:105]
	v_mfma_f32_16x16x32_bf16 v[106:109], v[222:225], v[214:217], v[106:109]
	ds_read_b128 v[194:197], v160 offset:448
	ds_read_b128 v[198:201], v160 offset:17088
	ds_read_b128 v[202:205], v226 offset:448
	s_and_saveexec_b64 s[24:25], s[64:65]
	ds_read_b128 v[206:209], v227 offset:448
	s_or_b64 exec, exec, s[24:25]
	s_waitcnt lgkmcnt(4)
	v_mfma_f32_16x16x32_bf16 v[110:113], v[126:129], v[118:121], v[110:113]
	v_mfma_f32_16x16x32_bf16 v[114:117], v[130:133], v[118:121], v[114:117]
	v_mfma_f32_16x16x32_bf16 v[102:105], v[126:129], v[122:125], v[102:105]
	v_mfma_f32_16x16x32_bf16 v[106:109], v[130:133], v[122:125], v[106:109]
	ds_read_b128 v[210:213], v160 offset:512
	ds_read_b128 v[214:217], v160 offset:17152
	ds_read_b128 v[218:221], v226 offset:512
	s_and_saveexec_b64 s[24:25], s[64:65]
	ds_read_b128 v[222:225], v227 offset:512
	s_or_b64 exec, exec, s[24:25]
	s_waitcnt lgkmcnt(4)
	v_mfma_f32_16x16x32_bf16 v[110:113], v[202:205], v[194:197], v[110:113]
	v_mfma_f32_16x16x32_bf16 v[114:117], v[206:209], v[194:197], v[114:117]
	v_mfma_f32_16x16x32_bf16 v[102:105], v[202:205], v[198:201], v[102:105]
	v_mfma_f32_16x16x32_bf16 v[106:109], v[206:209], v[198:201], v[106:109]
	ds_read_b128 v[118:121], v160 offset:576
	ds_read_b128 v[122:125], v160 offset:17216
	ds_read_b128 v[126:129], v226 offset:576
	s_and_saveexec_b64 s[24:25], s[64:65]
	ds_read_b128 v[130:133], v227 offset:576
	s_or_b64 exec, exec, s[24:25]
	s_waitcnt lgkmcnt(4)
	v_mfma_f32_16x16x32_bf16 v[110:113], v[218:221], v[210:213], v[110:113]
	v_mfma_f32_16x16x32_bf16 v[114:117], v[222:225], v[210:213], v[114:117]
	v_mfma_f32_16x16x32_bf16 v[102:105], v[218:221], v[214:217], v[102:105]
	v_mfma_f32_16x16x32_bf16 v[106:109], v[222:225], v[214:217], v[106:109]
	ds_read_b128 v[194:197], v160 offset:640
	ds_read_b128 v[198:201], v160 offset:17280
	ds_read_b128 v[202:205], v226 offset:640
	s_and_saveexec_b64 s[24:25], s[64:65]
	ds_read_b128 v[206:209], v227 offset:640
	s_or_b64 exec, exec, s[24:25]
	s_waitcnt lgkmcnt(4)
	v_mfma_f32_16x16x32_bf16 v[110:113], v[126:129], v[118:121], v[110:113]
	v_mfma_f32_16x16x32_bf16 v[114:117], v[130:133], v[118:121], v[114:117]
	v_mfma_f32_16x16x32_bf16 v[102:105], v[126:129], v[122:125], v[102:105]
	v_mfma_f32_16x16x32_bf16 v[106:109], v[130:133], v[122:125], v[106:109]
	ds_read_b128 v[210:213], v160 offset:704
	ds_read_b128 v[214:217], v160 offset:17344
	ds_read_b128 v[218:221], v226 offset:704
	s_and_saveexec_b64 s[24:25], s[64:65]
	ds_read_b128 v[222:225], v227 offset:704
	s_or_b64 exec, exec, s[24:25]
	s_waitcnt lgkmcnt(4)
	v_mfma_f32_16x16x32_bf16 v[110:113], v[202:205], v[194:197], v[110:113]
	v_mfma_f32_16x16x32_bf16 v[114:117], v[206:209], v[194:197], v[114:117]
	v_mfma_f32_16x16x32_bf16 v[102:105], v[202:205], v[198:201], v[102:105]
	v_mfma_f32_16x16x32_bf16 v[106:109], v[206:209], v[198:201], v[106:109]
	ds_read_b128 v[118:121], v160 offset:768
	ds_read_b128 v[122:125], v160 offset:17408
	ds_read_b128 v[126:129], v226 offset:768
	s_and_saveexec_b64 s[24:25], s[64:65]
	ds_read_b128 v[130:133], v227 offset:768
	s_or_b64 exec, exec, s[24:25]
	s_waitcnt lgkmcnt(4)
	v_mfma_f32_16x16x32_bf16 v[110:113], v[218:221], v[210:213], v[110:113]
	v_mfma_f32_16x16x32_bf16 v[114:117], v[222:225], v[210:213], v[114:117]
	v_mfma_f32_16x16x32_bf16 v[102:105], v[218:221], v[214:217], v[102:105]
	v_mfma_f32_16x16x32_bf16 v[106:109], v[222:225], v[214:217], v[106:109]
	ds_read_b128 v[194:197], v160 offset:832
	ds_read_b128 v[198:201], v160 offset:17472
	ds_read_b128 v[202:205], v226 offset:832
	s_and_saveexec_b64 s[24:25], s[64:65]
	ds_read_b128 v[206:209], v227 offset:832
	s_or_b64 exec, exec, s[24:25]
	s_waitcnt lgkmcnt(4)
	v_mfma_f32_16x16x32_bf16 v[110:113], v[126:129], v[118:121], v[110:113]
	v_mfma_f32_16x16x32_bf16 v[114:117], v[130:133], v[118:121], v[114:117]
	v_mfma_f32_16x16x32_bf16 v[102:105], v[126:129], v[122:125], v[102:105]
	v_mfma_f32_16x16x32_bf16 v[106:109], v[130:133], v[122:125], v[106:109]
	ds_read_b128 v[210:213], v160 offset:896
	ds_read_b128 v[214:217], v160 offset:17536
	ds_read_b128 v[218:221], v226 offset:896
	s_and_saveexec_b64 s[24:25], s[64:65]
	ds_read_b128 v[222:225], v227 offset:896
	s_or_b64 exec, exec, s[24:25]
	s_waitcnt lgkmcnt(4)
	v_mfma_f32_16x16x32_bf16 v[110:113], v[202:205], v[194:197], v[110:113]
	v_mfma_f32_16x16x32_bf16 v[114:117], v[206:209], v[194:197], v[114:117]
	v_mfma_f32_16x16x32_bf16 v[102:105], v[202:205], v[198:201], v[102:105]
	v_mfma_f32_16x16x32_bf16 v[106:109], v[206:209], v[198:201], v[106:109]
	ds_read_b128 v[118:121], v160 offset:960
	ds_read_b128 v[122:125], v160 offset:17600
	ds_read_b128 v[126:129], v226 offset:960
	s_and_saveexec_b64 s[24:25], s[64:65]
	ds_read_b128 v[130:133], v227 offset:960
	s_or_b64 exec, exec, s[24:25]
	s_waitcnt lgkmcnt(4)
	v_mfma_f32_16x16x32_bf16 v[110:113], v[218:221], v[210:213], v[110:113]
	v_mfma_f32_16x16x32_bf16 v[114:117], v[222:225], v[210:213], v[114:117]
	v_mfma_f32_16x16x32_bf16 v[102:105], v[218:221], v[214:217], v[102:105]
	v_mfma_f32_16x16x32_bf16 v[106:109], v[222:225], v[214:217], v[106:109]
	ds_read_b128 v[194:197], v192
	ds_read_b128 v[198:201], v161
	ds_read_b128 v[202:205], v161 offset:2304
	ds_read_b128 v[206:209], v192 offset:64
	ds_read_b128 v[226:229], v161 offset:64
	ds_read_b128 v[230:233], v161 offset:2368
	s_waitcnt lgkmcnt(6)
	v_mfma_f32_16x16x32_bf16 v[110:113], v[126:129], v[118:121], v[110:113]
	v_mfma_f32_16x16x32_bf16 v[114:117], v[130:133], v[118:121], v[114:117]
	v_mfma_f32_16x16x32_bf16 v[102:105], v[126:129], v[122:125], v[102:105]
	v_mfma_f32_16x16x32_bf16 v[106:109], v[130:133], v[122:125], v[106:109]
	s_waitcnt lgkmcnt(4)
	v_mfma_f32_16x16x32_bf16 v[214:217], v[194:197], v[198:201], 0
	s_waitcnt lgkmcnt(3)
	v_mfma_f32_16x16x32_bf16 v[210:213], v[194:197], v[202:205], 0
	s_waitcnt lgkmcnt(1)
	v_mfma_f32_16x16x32_bf16 v[214:217], v[206:209], v[226:229], v[214:217]
	s_waitcnt lgkmcnt(0)
	v_mfma_f32_16x16x32_bf16 v[210:213], v[206:209], v[230:233], v[210:213]
	s_nop 1
	ds_read2st64_b32 v[108:109], v173 offset1:2
	s_lshl_b32 s24, s30, 6
	s_add_i32 s24, s24, s18
	s_movk_i32 s31, 0x6000
	s_movk_i32 s34, 0x4000
	s_mov_b32 s35, 0x10000
	s_waitcnt lgkmcnt(0)
	v_fmac_f32_e32 v109, v108, v114
	v_max_f32_e64 v109, |v109|, 1.0
	v_rcp_f32_e32 v114, v109
	s_nop 2
	v_pk_fma_f32 v[110:111], v[110:111], v[108:109], v[214:215] op_sel_hi:[1,0,1]
	v_pk_fma_f32 v[108:109], v[112:113], v[108:109], v[216:217] op_sel_hi:[1,0,1]
	v_mul_f32_e64 v110, v110, v114
	v_mul_f32_e64 v111, v111, v114
	v_pk_mul_f32 v[108:109], v[108:109], v[114:115] op_sel_hi:[1,0]
	v_cvt_pk_bf16_f32 v110, v110, v111
	v_cvt_pk_bf16_f32 v111, v108, v109
	v_or_b32_e32 v108, s24, v155
	v_lshlrev_b32_e32 v108, 13, v108
	v_mov_b32_e32 v109, v0
	v_lshl_add_u64 v[108:109], v[150:151], 0, v[108:109]
	global_store_dwordx2 v[108:109], v[110:111], off
	v_mov_b32_e32 v108, v106
	ds_read2st64_b32 v[106:107], v175 offset1:2
	s_waitcnt lgkmcnt(0)
	v_fmac_f32_e32 v107, v106, v108
	v_max_f32_e64 v107, |v107|, 1.0
	v_rcp_f32_e32 v108, v107
	v_pk_fma_f32 v[102:103], v[102:103], v[106:107], v[210:211] op_sel_hi:[1,0,1]
	v_pk_fma_f32 v[104:105], v[104:105], v[106:107], v[212:213] op_sel_hi:[1,0,1]
	v_pk_mul_f32 v[102:103], v[102:103], v[108:109] op_sel_hi:[1,0]
	v_pk_mul_f32 v[104:105], v[104:105], v[108:109] op_sel_hi:[1,0]
	v_cvt_pk_bf16_f32 v102, v102, v103
	v_cvt_pk_bf16_f32 v103, v104, v105
	v_or_b32_e32 v104, s24, v174
	v_lshlrev_b32_e32 v104, 13, v104
	v_mov_b32_e32 v105, v0
	v_lshl_add_u64 v[104:105], v[150:151], 0, v[104:105]
	global_store_dwordx2 v[104:105], v[102:103], off
